# P7 epilogue hff stores written through (sc0 sc1) so the following grid barrier's L2 write-back is cheaper
# speedup vs baseline: 1.0044x; 1.0044x over previous
.LBB0_977:
	v_lshl_add_u32 v146, s24, 8, v148
	v_mbcnt_hi_u32_b32 v170, -1, v192
	v_lshrrev_b32_e32 v171, 4, v170
	v_lshlrev_b32_e32 v171, 4, v171
	v_lshl_add_u32 v171, v146, 6, v171
	v_add_u32_e32 v172, 0x2000, v171
	v_xor_b32_e32 v210, 16, v170
	v_lshlrev_b32_e32 v210, 2, v210
	v_xor_b32_e32 v211, 32, v170
	v_lshlrev_b32_e32 v211, 2, v211
	global_load_dwordx4 v[174:177], v171, s[22:23]
	global_load_dwordx4 v[178:181], v171, s[22:23] offset:1024
	global_load_dwordx4 v[182:185], v171, s[22:23] offset:2048
	global_load_dwordx4 v[186:189], v171, s[22:23] offset:3072
	global_load_dwordx4 v[194:197], v172, s[22:23]
	global_load_dwordx4 v[198:201], v172, s[22:23] offset:1024
	global_load_dwordx4 v[202:205], v172, s[22:23] offset:2048
	global_load_dwordx4 v[206:209], v172, s[22:23] offset:3072
	s_waitcnt vmcnt(0)
	v_add_f32_e32 v174, v174, v175
	v_add_f32_e32 v176, v176, v177
	v_add_f32_e32 v178, v178, v179
	v_add_f32_e32 v180, v180, v181
	v_add_f32_e32 v182, v182, v183
	v_add_f32_e32 v184, v184, v185
	v_add_f32_e32 v186, v186, v187
	v_add_f32_e32 v188, v188, v189
	v_add_f32_e32 v194, v194, v195
	v_add_f32_e32 v196, v196, v197
	v_add_f32_e32 v198, v198, v199
	v_add_f32_e32 v200, v200, v201
	v_add_f32_e32 v202, v202, v203
	v_add_f32_e32 v204, v204, v205
	v_add_f32_e32 v206, v206, v207
	v_add_f32_e32 v208, v208, v209
	v_add_f32_e32 v174, v174, v176
	v_add_f32_e32 v178, v178, v180
	v_add_f32_e32 v182, v182, v184
	v_add_f32_e32 v186, v186, v188
	v_add_f32_e32 v194, v194, v196
	v_add_f32_e32 v198, v198, v200
	v_add_f32_e32 v202, v202, v204
	v_add_f32_e32 v206, v206, v208
	ds_bpermute_b32 v212, v210, v174
	ds_bpermute_b32 v213, v210, v178
	ds_bpermute_b32 v214, v210, v182
	ds_bpermute_b32 v215, v210, v186
	ds_bpermute_b32 v216, v210, v194
	ds_bpermute_b32 v217, v210, v198
	ds_bpermute_b32 v218, v210, v202
	ds_bpermute_b32 v219, v210, v206
	s_waitcnt lgkmcnt(0)
	v_add_f32_e32 v174, v174, v212
	v_add_f32_e32 v178, v178, v213
	v_add_f32_e32 v182, v182, v214
	v_add_f32_e32 v186, v186, v215
	v_add_f32_e32 v194, v194, v216
	v_add_f32_e32 v198, v198, v217
	v_add_f32_e32 v202, v202, v218
	v_add_f32_e32 v206, v206, v219
	ds_bpermute_b32 v212, v211, v174
	ds_bpermute_b32 v213, v211, v178
	ds_bpermute_b32 v214, v211, v182
	ds_bpermute_b32 v215, v211, v186
	ds_bpermute_b32 v216, v211, v194
	ds_bpermute_b32 v217, v211, v198
	ds_bpermute_b32 v218, v211, v202
	ds_bpermute_b32 v219, v211, v206
	s_waitcnt lgkmcnt(0)
	v_add_f32_e32 v174, v174, v212
	v_add_f32_e32 v178, v178, v213
	v_add_f32_e32 v182, v182, v214
	v_add_f32_e32 v186, v186, v215
	v_add_f32_e32 v194, v194, v216
	v_add_f32_e32 v198, v198, v217
	v_add_f32_e32 v202, v202, v218
	v_add_f32_e32 v206, v206, v219
	v_fmamk_f32 v220, v174, 0x3a800000, v153
	v_fmamk_f32 v221, v178, 0x3a800000, v153
	v_fmamk_f32 v222, v182, 0x3a800000, v153
	v_fmamk_f32 v223, v186, 0x3a800000, v153
	v_fmamk_f32 v224, v194, 0x3a800000, v153
	v_fmamk_f32 v225, v198, 0x3a800000, v153
	v_fmamk_f32 v226, v202, 0x3a800000, v153
	v_fmamk_f32 v227, v206, 0x3a800000, v153
	v_rsq_f32_e32 v220, v220
	v_rsq_f32_e32 v221, v221
	v_rsq_f32_e32 v222, v222
	v_rsq_f32_e32 v223, v223
	v_rsq_f32_e32 v224, v224
	v_rsq_f32_e32 v225, v225
	v_rsq_f32_e32 v226, v226
	v_rsq_f32_e32 v227, v227
	s_nop 0
	s_lshl_b32 s24, s25, 7
	s_ashr_i32 s25, s24, 31
	s_lshl_b64 s[24:25], s[24:25], 1
	s_andn2_b64 vcc, exec, s[40:41]
	v_mov_b32_e32 v154, v220
	s_nop 0
	v_pk_mul_f32 v[124:125], v[124:125], v[154:155] op_sel_hi:[1,0]
	s_nop 0
	v_mul_f32_e32 v147, 0xbfb8aa3b, v124
	v_exp_f32_e32 v147, v147
	v_pk_mul_f32 v[116:117], v[116:117], v[154:155] op_sel_hi:[1,0]
	v_pk_mul_f32 v[118:119], v[118:119], v[154:155] op_sel_hi:[1,0]
	v_pk_mul_f32 v[120:121], v[120:121], v[154:155] op_sel_hi:[1,0]
	v_add_f32_e32 v147, 1.0, v147
	v_rcp_f32_e32 v156, v147
	v_mul_f32_e32 v147, 0xbfb8aa3b, v125
	v_exp_f32_e32 v147, v147
	v_pk_mul_f32 v[112:113], v[112:113], v[154:155] op_sel_hi:[1,0]
	v_pk_mul_f32 v[114:115], v[114:115], v[154:155] op_sel_hi:[1,0]
	v_add_f32_e32 v147, 1.0, v147
	v_rcp_f32_e32 v157, v147
	s_nop 0
	v_pk_mul_f32 v[124:125], v[124:125], v[156:157]
	s_nop 0
	v_pk_mul_f32 v[116:117], v[116:117], v[124:125]
	v_pk_mul_f32 v[124:125], v[126:127], v[154:155] op_sel_hi:[1,0]
	s_nop 0
	v_mul_f32_e32 v126, 0xbfb8aa3b, v124
	v_mul_f32_e32 v127, 0xbfb8aa3b, v125
	v_exp_f32_e32 v126, v126
	v_exp_f32_e32 v127, v127
	v_add_f32_e32 v126, 1.0, v126
	v_add_f32_e32 v127, 1.0, v127
	v_rcp_f32_e32 v126, v126
	v_rcp_f32_e32 v127, v127
	s_nop 0
	v_pk_mul_f32 v[124:125], v[124:125], v[126:127]
	s_nop 0
	v_pk_mul_f32 v[118:119], v[118:119], v[124:125]
	v_mul_f32_e32 v124, 0xbfb8aa3b, v120
	v_mul_f32_e32 v125, 0xbfb8aa3b, v121
	v_exp_f32_e32 v124, v124
	v_exp_f32_e32 v125, v125
	v_add_f32_e32 v124, 1.0, v124
	v_add_f32_e32 v125, 1.0, v125
	v_rcp_f32_e32 v124, v124
	v_rcp_f32_e32 v125, v125
	s_nop 0
	v_pk_mul_f32 v[120:121], v[120:121], v[124:125]
	s_nop 0
	v_pk_mul_f32 v[112:113], v[112:113], v[120:121]
	v_pk_mul_f32 v[120:121], v[122:123], v[154:155] op_sel_hi:[1,0]
	s_nop 0
	v_mul_f32_e32 v122, 0xbfb8aa3b, v120
	v_mul_f32_e32 v123, 0xbfb8aa3b, v121
	v_exp_f32_e32 v122, v122
	v_exp_f32_e32 v123, v123
	v_add_f32_e32 v122, 1.0, v122
	v_add_f32_e32 v123, 1.0, v123
	v_rcp_f32_e32 v122, v122
	v_rcp_f32_e32 v123, v123
	s_nop 0
	v_pk_mul_f32 v[120:121], v[120:121], v[122:123]
	s_nop 0
	v_pk_mul_f32 v[120:121], v[114:115], v[120:121]
	v_cvt_pk_bf16_f32 v114, v116, v117
	v_cvt_pk_bf16_f32 v116, v112, v113
	v_mov_b64_e32 v[112:113], s[80:81]
	v_cvt_pk_bf16_f32 v115, v118, v119
	v_mad_i64_i32 v[118:119], s[26:27], v146, s45, v[112:113]
	v_lshl_add_u64 v[118:119], v[118:119], 0, s[24:25]
	v_lshl_add_u64 v[118:119], v[118:119], 0, s[8:9]
	v_cvt_pk_bf16_f32 v117, v120, v121
	v_lshl_add_u64 v[118:119], v[118:119], 0, v[136:137]
	global_store_dwordx4 v[118:119], v[114:117], off sc0 sc1
	s_nop 1
	v_or_b32_e32 v114, 16, v146
	v_mov_b32_e32 v116, v221
	s_nop 0
	v_pk_mul_f32 v[108:109], v[108:109], v[116:117] op_sel_hi:[1,0]
	s_nop 0
	v_mul_f32_e32 v115, 0xbfb8aa3b, v108
	v_exp_f32_e32 v115, v115
	v_pk_mul_f32 v[100:101], v[100:101], v[116:117] op_sel_hi:[1,0]
	v_pk_mul_f32 v[102:103], v[102:103], v[116:117] op_sel_hi:[1,0]
	v_pk_mul_f32 v[104:105], v[104:105], v[116:117] op_sel_hi:[1,0]
	v_add_f32_e32 v115, 1.0, v115
	v_rcp_f32_e32 v118, v115
	v_mul_f32_e32 v115, 0xbfb8aa3b, v109
	v_exp_f32_e32 v115, v115
	v_pk_mul_f32 v[96:97], v[96:97], v[116:117] op_sel_hi:[1,0]
	v_pk_mul_f32 v[98:99], v[98:99], v[116:117] op_sel_hi:[1,0]
	v_add_f32_e32 v115, 1.0, v115
	v_rcp_f32_e32 v119, v115
	s_nop 0
	v_pk_mul_f32 v[108:109], v[108:109], v[118:119]
	s_nop 0
	v_pk_mul_f32 v[100:101], v[100:101], v[108:109]
	v_pk_mul_f32 v[108:109], v[110:111], v[116:117] op_sel_hi:[1,0]
	s_nop 0
	v_mul_f32_e32 v110, 0xbfb8aa3b, v108
	v_mul_f32_e32 v111, 0xbfb8aa3b, v109
	v_exp_f32_e32 v110, v110
	v_exp_f32_e32 v111, v111
	v_add_f32_e32 v110, 1.0, v110
	v_add_f32_e32 v111, 1.0, v111
	v_rcp_f32_e32 v110, v110
	v_rcp_f32_e32 v111, v111
	s_nop 0
	v_pk_mul_f32 v[108:109], v[108:109], v[110:111]
	s_nop 0
	v_pk_mul_f32 v[102:103], v[102:103], v[108:109]
	v_mul_f32_e32 v108, 0xbfb8aa3b, v104
	v_mul_f32_e32 v109, 0xbfb8aa3b, v105
	v_exp_f32_e32 v108, v108
	v_exp_f32_e32 v109, v109
	v_add_f32_e32 v108, 1.0, v108
	v_add_f32_e32 v109, 1.0, v109
	v_rcp_f32_e32 v108, v108
	v_rcp_f32_e32 v109, v109
	s_nop 0
	v_pk_mul_f32 v[104:105], v[104:105], v[108:109]
	s_nop 0
	v_pk_mul_f32 v[104:105], v[96:97], v[104:105]
	v_pk_mul_f32 v[96:97], v[106:107], v[116:117] op_sel_hi:[1,0]
	s_nop 0
	v_mul_f32_e32 v106, 0xbfb8aa3b, v96
	v_mul_f32_e32 v107, 0xbfb8aa3b, v97
	v_exp_f32_e32 v106, v106
	v_exp_f32_e32 v107, v107
	v_add_f32_e32 v106, 1.0, v106
	v_add_f32_e32 v107, 1.0, v107
	v_rcp_f32_e32 v106, v106
	v_rcp_f32_e32 v107, v107
	s_nop 0
	v_pk_mul_f32 v[96:97], v[96:97], v[106:107]
	s_nop 0
	v_pk_mul_f32 v[106:107], v[98:99], v[96:97]
	v_cvt_pk_bf16_f32 v96, v100, v101
	v_mad_i64_i32 v[100:101], s[26:27], v114, s45, v[112:113]
	v_lshl_add_u64 v[100:101], v[100:101], 0, s[24:25]
	v_lshl_add_u64 v[100:101], v[100:101], 0, s[8:9]
	v_cvt_pk_bf16_f32 v97, v102, v103
	v_cvt_pk_bf16_f32 v98, v104, v105
	v_cvt_pk_bf16_f32 v99, v106, v107
	v_lshl_add_u64 v[100:101], v[100:101], 0, v[136:137]
	global_store_dwordx4 v[100:101], v[96:99], off sc0 sc1
	s_nop 1
	v_or_b32_e32 v96, 32, v146
	v_mov_b32_e32 v98, v222
	s_nop 0
	v_pk_mul_f32 v[92:93], v[92:93], v[98:99] op_sel_hi:[1,0]
	s_nop 0
	v_mul_f32_e32 v97, 0xbfb8aa3b, v92
	v_exp_f32_e32 v97, v97
	v_pk_mul_f32 v[84:85], v[84:85], v[98:99] op_sel_hi:[1,0]
	v_pk_mul_f32 v[86:87], v[86:87], v[98:99] op_sel_hi:[1,0]
	v_pk_mul_f32 v[88:89], v[88:89], v[98:99] op_sel_hi:[1,0]
	v_add_f32_e32 v97, 1.0, v97
	v_rcp_f32_e32 v100, v97
	v_mul_f32_e32 v97, 0xbfb8aa3b, v93
	v_exp_f32_e32 v97, v97
	v_pk_mul_f32 v[80:81], v[80:81], v[98:99] op_sel_hi:[1,0]
	v_pk_mul_f32 v[82:83], v[82:83], v[98:99] op_sel_hi:[1,0]
	v_add_f32_e32 v97, 1.0, v97
	v_rcp_f32_e32 v101, v97
	s_nop 0
	v_pk_mul_f32 v[92:93], v[92:93], v[100:101]
	s_nop 0
	v_pk_mul_f32 v[84:85], v[84:85], v[92:93]
	v_pk_mul_f32 v[92:93], v[94:95], v[98:99] op_sel_hi:[1,0]
	s_nop 0
	v_mul_f32_e32 v94, 0xbfb8aa3b, v92
	v_mul_f32_e32 v95, 0xbfb8aa3b, v93
	v_exp_f32_e32 v94, v94
	v_exp_f32_e32 v95, v95
	v_add_f32_e32 v94, 1.0, v94
	v_add_f32_e32 v95, 1.0, v95
	v_rcp_f32_e32 v94, v94
	v_rcp_f32_e32 v95, v95
	s_nop 0
	v_pk_mul_f32 v[92:93], v[92:93], v[94:95]
	s_nop 0
	v_pk_mul_f32 v[86:87], v[86:87], v[92:93]
	v_mul_f32_e32 v92, 0xbfb8aa3b, v88
	v_mul_f32_e32 v93, 0xbfb8aa3b, v89
	v_exp_f32_e32 v92, v92
	v_exp_f32_e32 v93, v93
	v_add_f32_e32 v92, 1.0, v92
	v_add_f32_e32 v93, 1.0, v93
	v_rcp_f32_e32 v92, v92
	v_rcp_f32_e32 v93, v93
	s_nop 0
	v_pk_mul_f32 v[88:89], v[88:89], v[92:93]
	s_nop 0
	v_pk_mul_f32 v[88:89], v[80:81], v[88:89]
	v_pk_mul_f32 v[80:81], v[90:91], v[98:99] op_sel_hi:[1,0]
	s_nop 0
	v_mul_f32_e32 v90, 0xbfb8aa3b, v80
	v_mul_f32_e32 v91, 0xbfb8aa3b, v81
	v_exp_f32_e32 v90, v90
	v_exp_f32_e32 v91, v91
	v_add_f32_e32 v90, 1.0, v90
	v_add_f32_e32 v91, 1.0, v91
	v_rcp_f32_e32 v90, v90
	v_rcp_f32_e32 v91, v91
	s_nop 0
	v_pk_mul_f32 v[80:81], v[80:81], v[90:91]
	s_nop 0
	v_pk_mul_f32 v[90:91], v[82:83], v[80:81]
	v_cvt_pk_bf16_f32 v80, v84, v85
	v_mad_i64_i32 v[84:85], s[26:27], v96, s45, v[112:113]
	v_lshl_add_u64 v[84:85], v[84:85], 0, s[24:25]
	v_lshl_add_u64 v[84:85], v[84:85], 0, s[8:9]
	v_cvt_pk_bf16_f32 v81, v86, v87
	v_cvt_pk_bf16_f32 v82, v88, v89
	v_cvt_pk_bf16_f32 v83, v90, v91
	v_lshl_add_u64 v[84:85], v[84:85], 0, v[136:137]
	global_store_dwordx4 v[84:85], v[80:83], off sc0 sc1
	s_nop 1
	v_or_b32_e32 v80, 48, v146
	v_mov_b32_e32 v82, v223
	s_nop 0
	v_pk_mul_f32 v[76:77], v[76:77], v[82:83] op_sel_hi:[1,0]
	s_nop 0
	v_mul_f32_e32 v81, 0xbfb8aa3b, v76
	v_exp_f32_e32 v81, v81
	v_pk_mul_f32 v[68:69], v[68:69], v[82:83] op_sel_hi:[1,0]
	v_pk_mul_f32 v[70:71], v[70:71], v[82:83] op_sel_hi:[1,0]
	v_pk_mul_f32 v[72:73], v[72:73], v[82:83] op_sel_hi:[1,0]
	v_add_f32_e32 v81, 1.0, v81
	v_rcp_f32_e32 v84, v81
	v_mul_f32_e32 v81, 0xbfb8aa3b, v77
	v_exp_f32_e32 v81, v81
	v_pk_mul_f32 v[64:65], v[64:65], v[82:83] op_sel_hi:[1,0]
	v_pk_mul_f32 v[66:67], v[66:67], v[82:83] op_sel_hi:[1,0]
	v_add_f32_e32 v81, 1.0, v81
	v_rcp_f32_e32 v85, v81
	s_nop 0
	v_pk_mul_f32 v[76:77], v[76:77], v[84:85]
	s_nop 0
	v_pk_mul_f32 v[68:69], v[68:69], v[76:77]
	v_pk_mul_f32 v[76:77], v[78:79], v[82:83] op_sel_hi:[1,0]
	s_nop 0
	v_mul_f32_e32 v78, 0xbfb8aa3b, v76
	v_mul_f32_e32 v79, 0xbfb8aa3b, v77
	v_exp_f32_e32 v78, v78
	v_exp_f32_e32 v79, v79
	v_add_f32_e32 v78, 1.0, v78
	v_add_f32_e32 v79, 1.0, v79
	v_rcp_f32_e32 v78, v78
	v_rcp_f32_e32 v79, v79
	s_nop 0
	v_pk_mul_f32 v[76:77], v[76:77], v[78:79]
	s_nop 0
	v_pk_mul_f32 v[70:71], v[70:71], v[76:77]
	v_mul_f32_e32 v76, 0xbfb8aa3b, v72
	v_mul_f32_e32 v77, 0xbfb8aa3b, v73
	v_exp_f32_e32 v76, v76
	v_exp_f32_e32 v77, v77
	v_add_f32_e32 v76, 1.0, v76
	v_add_f32_e32 v77, 1.0, v77
	v_rcp_f32_e32 v76, v76
	v_rcp_f32_e32 v77, v77
	s_nop 0
	v_pk_mul_f32 v[72:73], v[72:73], v[76:77]
	s_nop 0
	v_pk_mul_f32 v[72:73], v[64:65], v[72:73]
	v_pk_mul_f32 v[64:65], v[74:75], v[82:83] op_sel_hi:[1,0]
	s_nop 0
	v_mul_f32_e32 v74, 0xbfb8aa3b, v64
	v_mul_f32_e32 v75, 0xbfb8aa3b, v65
	v_exp_f32_e32 v74, v74
	v_exp_f32_e32 v75, v75
	v_add_f32_e32 v74, 1.0, v74
	v_add_f32_e32 v75, 1.0, v75
	v_rcp_f32_e32 v74, v74
	v_rcp_f32_e32 v75, v75
	s_nop 0
	v_pk_mul_f32 v[64:65], v[64:65], v[74:75]
	s_nop 0
	v_pk_mul_f32 v[74:75], v[66:67], v[64:65]
	v_cvt_pk_bf16_f32 v64, v68, v69
	v_mad_i64_i32 v[68:69], s[26:27], v80, s45, v[112:113]
	v_lshl_add_u64 v[68:69], v[68:69], 0, s[24:25]
	v_lshl_add_u64 v[68:69], v[68:69], 0, s[8:9]
	v_cvt_pk_bf16_f32 v65, v70, v71
	v_cvt_pk_bf16_f32 v66, v72, v73
	v_cvt_pk_bf16_f32 v67, v74, v75
	v_lshl_add_u64 v[68:69], v[68:69], 0, v[136:137]
	global_store_dwordx4 v[68:69], v[64:67], off sc0 sc1
	s_nop 1
	v_add_u32_e32 v64, 0x80, v146
	v_mov_b32_e32 v66, v224
	s_nop 0
	v_pk_mul_f32 v[60:61], v[60:61], v[66:67] op_sel_hi:[1,0]
	s_nop 0
	v_mul_f32_e32 v65, 0xbfb8aa3b, v60
	v_exp_f32_e32 v65, v65
	v_pk_mul_f32 v[52:53], v[52:53], v[66:67] op_sel_hi:[1,0]
	v_pk_mul_f32 v[54:55], v[54:55], v[66:67] op_sel_hi:[1,0]
	v_pk_mul_f32 v[56:57], v[56:57], v[66:67] op_sel_hi:[1,0]
	v_add_f32_e32 v65, 1.0, v65
	v_rcp_f32_e32 v68, v65
	v_mul_f32_e32 v65, 0xbfb8aa3b, v61
	v_exp_f32_e32 v65, v65
	v_pk_mul_f32 v[48:49], v[48:49], v[66:67] op_sel_hi:[1,0]
	v_pk_mul_f32 v[50:51], v[50:51], v[66:67] op_sel_hi:[1,0]
	v_add_f32_e32 v65, 1.0, v65
	v_rcp_f32_e32 v69, v65
	s_nop 0
	v_pk_mul_f32 v[60:61], v[60:61], v[68:69]
	s_nop 0
	v_pk_mul_f32 v[52:53], v[52:53], v[60:61]
	v_pk_mul_f32 v[60:61], v[62:63], v[66:67] op_sel_hi:[1,0]
	s_nop 0
	v_mul_f32_e32 v62, 0xbfb8aa3b, v60
	v_mul_f32_e32 v63, 0xbfb8aa3b, v61
	v_exp_f32_e32 v62, v62
	v_exp_f32_e32 v63, v63
	v_add_f32_e32 v62, 1.0, v62
	v_add_f32_e32 v63, 1.0, v63
	v_rcp_f32_e32 v62, v62
	v_rcp_f32_e32 v63, v63
	s_nop 0
	v_pk_mul_f32 v[60:61], v[60:61], v[62:63]
	s_nop 0
	v_pk_mul_f32 v[54:55], v[54:55], v[60:61]
	v_mul_f32_e32 v60, 0xbfb8aa3b, v56
	v_mul_f32_e32 v61, 0xbfb8aa3b, v57
	v_exp_f32_e32 v60, v60
	v_exp_f32_e32 v61, v61
	v_add_f32_e32 v60, 1.0, v60
	v_add_f32_e32 v61, 1.0, v61
	v_rcp_f32_e32 v60, v60
	v_rcp_f32_e32 v61, v61
	s_nop 0
	v_pk_mul_f32 v[56:57], v[56:57], v[60:61]
	s_nop 0
	v_pk_mul_f32 v[56:57], v[48:49], v[56:57]
	v_pk_mul_f32 v[48:49], v[58:59], v[66:67] op_sel_hi:[1,0]
	s_nop 0
	v_mul_f32_e32 v58, 0xbfb8aa3b, v48
	v_mul_f32_e32 v59, 0xbfb8aa3b, v49
	v_exp_f32_e32 v58, v58
	v_exp_f32_e32 v59, v59
	v_add_f32_e32 v58, 1.0, v58
	v_add_f32_e32 v59, 1.0, v59
	v_rcp_f32_e32 v58, v58
	v_rcp_f32_e32 v59, v59
	s_nop 0
	v_pk_mul_f32 v[48:49], v[48:49], v[58:59]
	s_nop 0
	v_pk_mul_f32 v[58:59], v[50:51], v[48:49]
	v_cvt_pk_bf16_f32 v48, v52, v53
	v_mad_i64_i32 v[52:53], s[26:27], v64, s45, v[112:113]
	v_lshl_add_u64 v[52:53], v[52:53], 0, s[24:25]
	v_lshl_add_u64 v[52:53], v[52:53], 0, s[8:9]
	v_cvt_pk_bf16_f32 v49, v54, v55
	v_cvt_pk_bf16_f32 v50, v56, v57
	v_cvt_pk_bf16_f32 v51, v58, v59
	v_lshl_add_u64 v[52:53], v[52:53], 0, v[136:137]
	global_store_dwordx4 v[52:53], v[48:51], off sc0 sc1
	s_nop 1
	v_add_u32_e32 v48, 0x90, v146
	v_mov_b32_e32 v50, v225
	s_nop 0
	v_pk_mul_f32 v[44:45], v[44:45], v[50:51] op_sel_hi:[1,0]
	s_nop 0
	v_mul_f32_e32 v49, 0xbfb8aa3b, v44
	v_exp_f32_e32 v49, v49
	v_pk_mul_f32 v[36:37], v[36:37], v[50:51] op_sel_hi:[1,0]
	v_pk_mul_f32 v[38:39], v[38:39], v[50:51] op_sel_hi:[1,0]
	v_pk_mul_f32 v[40:41], v[40:41], v[50:51] op_sel_hi:[1,0]
	v_add_f32_e32 v49, 1.0, v49
	v_rcp_f32_e32 v52, v49
	v_mul_f32_e32 v49, 0xbfb8aa3b, v45
	v_exp_f32_e32 v49, v49
	v_pk_mul_f32 v[32:33], v[32:33], v[50:51] op_sel_hi:[1,0]
	v_pk_mul_f32 v[34:35], v[34:35], v[50:51] op_sel_hi:[1,0]
	v_add_f32_e32 v49, 1.0, v49
	v_rcp_f32_e32 v53, v49
	s_nop 0
	v_pk_mul_f32 v[44:45], v[44:45], v[52:53]
	s_nop 0
	v_pk_mul_f32 v[36:37], v[36:37], v[44:45]
	v_pk_mul_f32 v[44:45], v[46:47], v[50:51] op_sel_hi:[1,0]
	s_nop 0
	v_mul_f32_e32 v46, 0xbfb8aa3b, v44
	v_mul_f32_e32 v47, 0xbfb8aa3b, v45
	v_exp_f32_e32 v46, v46
	v_exp_f32_e32 v47, v47
	v_add_f32_e32 v46, 1.0, v46
	v_add_f32_e32 v47, 1.0, v47
	v_rcp_f32_e32 v46, v46
	v_rcp_f32_e32 v47, v47
	s_nop 0
	v_pk_mul_f32 v[44:45], v[44:45], v[46:47]
	s_nop 0
	v_pk_mul_f32 v[38:39], v[38:39], v[44:45]
	v_mul_f32_e32 v44, 0xbfb8aa3b, v40
	v_mul_f32_e32 v45, 0xbfb8aa3b, v41
	v_exp_f32_e32 v44, v44
	v_exp_f32_e32 v45, v45
	v_add_f32_e32 v44, 1.0, v44
	v_add_f32_e32 v45, 1.0, v45
	v_rcp_f32_e32 v44, v44
	v_rcp_f32_e32 v45, v45
	s_nop 0
	v_pk_mul_f32 v[40:41], v[40:41], v[44:45]
	s_nop 0
	v_pk_mul_f32 v[40:41], v[32:33], v[40:41]
	v_pk_mul_f32 v[32:33], v[42:43], v[50:51] op_sel_hi:[1,0]
	s_nop 0
	v_mul_f32_e32 v42, 0xbfb8aa3b, v32
	v_mul_f32_e32 v43, 0xbfb8aa3b, v33
	v_exp_f32_e32 v42, v42
	v_exp_f32_e32 v43, v43
	v_add_f32_e32 v42, 1.0, v42
	v_add_f32_e32 v43, 1.0, v43
	v_rcp_f32_e32 v42, v42
	v_rcp_f32_e32 v43, v43
	s_nop 0
	v_pk_mul_f32 v[32:33], v[32:33], v[42:43]
	s_nop 0
	v_pk_mul_f32 v[42:43], v[34:35], v[32:33]
	v_cvt_pk_bf16_f32 v32, v36, v37
	v_mad_i64_i32 v[36:37], s[26:27], v48, s45, v[112:113]
	v_lshl_add_u64 v[36:37], v[36:37], 0, s[24:25]
	v_lshl_add_u64 v[36:37], v[36:37], 0, s[8:9]
	v_cvt_pk_bf16_f32 v33, v38, v39
	v_cvt_pk_bf16_f32 v34, v40, v41
	v_cvt_pk_bf16_f32 v35, v42, v43
	v_lshl_add_u64 v[36:37], v[36:37], 0, v[136:137]
	global_store_dwordx4 v[36:37], v[32:35], off sc0 sc1
	s_nop 1
	v_add_u32_e32 v32, 0xa0, v146
	v_mov_b32_e32 v34, v226
	s_nop 0
	v_pk_mul_f32 v[28:29], v[28:29], v[34:35] op_sel_hi:[1,0]
	s_nop 0
	v_mul_f32_e32 v33, 0xbfb8aa3b, v28
	v_exp_f32_e32 v33, v33
	v_pk_mul_f32 v[20:21], v[20:21], v[34:35] op_sel_hi:[1,0]
	v_pk_mul_f32 v[22:23], v[22:23], v[34:35] op_sel_hi:[1,0]
	v_pk_mul_f32 v[24:25], v[24:25], v[34:35] op_sel_hi:[1,0]
	v_add_f32_e32 v33, 1.0, v33
	v_rcp_f32_e32 v36, v33
	v_mul_f32_e32 v33, 0xbfb8aa3b, v29
	v_exp_f32_e32 v33, v33
	v_pk_mul_f32 v[16:17], v[16:17], v[34:35] op_sel_hi:[1,0]
	v_pk_mul_f32 v[18:19], v[18:19], v[34:35] op_sel_hi:[1,0]
	v_add_f32_e32 v33, 1.0, v33
	v_rcp_f32_e32 v37, v33
	s_nop 0
	v_pk_mul_f32 v[28:29], v[28:29], v[36:37]
	s_nop 0
	v_pk_mul_f32 v[20:21], v[20:21], v[28:29]
	v_pk_mul_f32 v[28:29], v[30:31], v[34:35] op_sel_hi:[1,0]
	s_nop 0
	v_mul_f32_e32 v30, 0xbfb8aa3b, v28
	v_mul_f32_e32 v31, 0xbfb8aa3b, v29
	v_exp_f32_e32 v30, v30
	v_exp_f32_e32 v31, v31
	v_add_f32_e32 v30, 1.0, v30
	v_add_f32_e32 v31, 1.0, v31
	v_rcp_f32_e32 v30, v30
	v_rcp_f32_e32 v31, v31
	s_nop 0
	v_pk_mul_f32 v[28:29], v[28:29], v[30:31]
	s_nop 0
	v_pk_mul_f32 v[22:23], v[22:23], v[28:29]
	v_mul_f32_e32 v28, 0xbfb8aa3b, v24
	v_mul_f32_e32 v29, 0xbfb8aa3b, v25
	v_exp_f32_e32 v28, v28
	v_exp_f32_e32 v29, v29
	v_add_f32_e32 v28, 1.0, v28
	v_add_f32_e32 v29, 1.0, v29
	v_rcp_f32_e32 v28, v28
	v_rcp_f32_e32 v29, v29
	s_nop 0
	v_pk_mul_f32 v[24:25], v[24:25], v[28:29]
	s_nop 0
	v_pk_mul_f32 v[24:25], v[16:17], v[24:25]
	v_pk_mul_f32 v[16:17], v[26:27], v[34:35] op_sel_hi:[1,0]
	s_nop 0
	v_mul_f32_e32 v26, 0xbfb8aa3b, v16
	v_mul_f32_e32 v27, 0xbfb8aa3b, v17
	v_exp_f32_e32 v26, v26
	v_exp_f32_e32 v27, v27
	v_add_f32_e32 v26, 1.0, v26
	v_add_f32_e32 v27, 1.0, v27
	v_rcp_f32_e32 v26, v26
	v_rcp_f32_e32 v27, v27
	s_nop 0
	v_pk_mul_f32 v[16:17], v[16:17], v[26:27]
	s_nop 0
	v_pk_mul_f32 v[26:27], v[18:19], v[16:17]
	v_cvt_pk_bf16_f32 v16, v20, v21
	v_mad_i64_i32 v[20:21], s[26:27], v32, s45, v[112:113]
	v_lshl_add_u64 v[20:21], v[20:21], 0, s[24:25]
	v_lshl_add_u64 v[20:21], v[20:21], 0, s[8:9]
	v_cvt_pk_bf16_f32 v17, v22, v23
	v_cvt_pk_bf16_f32 v18, v24, v25
	v_cvt_pk_bf16_f32 v19, v26, v27
	v_lshl_add_u64 v[20:21], v[20:21], 0, v[136:137]
	global_store_dwordx4 v[20:21], v[16:19], off sc0 sc1
	s_nop 1
	v_add_u32_e32 v16, 0xb0, v146
	v_mov_b32_e32 v18, v227
	s_nop 0
	v_pk_mul_f32 v[12:13], v[12:13], v[18:19] op_sel_hi:[1,0]
	s_nop 0
	v_mul_f32_e32 v17, 0xbfb8aa3b, v12
	v_exp_f32_e32 v17, v17
	v_pk_mul_f32 v[4:5], v[4:5], v[18:19] op_sel_hi:[1,0]
	v_pk_mul_f32 v[6:7], v[6:7], v[18:19] op_sel_hi:[1,0]
	v_pk_mul_f32 v[8:9], v[8:9], v[18:19] op_sel_hi:[1,0]
	v_add_f32_e32 v17, 1.0, v17
	v_rcp_f32_e32 v20, v17
	v_mul_f32_e32 v17, 0xbfb8aa3b, v13
	v_exp_f32_e32 v17, v17
	v_pk_mul_f32 v[0:1], v[0:1], v[18:19] op_sel_hi:[1,0]
	v_pk_mul_f32 v[2:3], v[2:3], v[18:19] op_sel_hi:[1,0]
	v_add_f32_e32 v17, 1.0, v17
	v_rcp_f32_e32 v21, v17
	s_nop 0
	v_pk_mul_f32 v[12:13], v[12:13], v[20:21]
	s_nop 0
	v_pk_mul_f32 v[4:5], v[4:5], v[12:13]
	v_pk_mul_f32 v[12:13], v[14:15], v[18:19] op_sel_hi:[1,0]
	s_nop 0
	v_mul_f32_e32 v14, 0xbfb8aa3b, v12
	v_mul_f32_e32 v15, 0xbfb8aa3b, v13
	v_exp_f32_e32 v14, v14
	v_exp_f32_e32 v15, v15
	v_add_f32_e32 v14, 1.0, v14
	v_add_f32_e32 v15, 1.0, v15
	v_rcp_f32_e32 v14, v14
	v_rcp_f32_e32 v15, v15
	s_nop 0
	v_pk_mul_f32 v[12:13], v[12:13], v[14:15]
	s_nop 0
	v_pk_mul_f32 v[6:7], v[6:7], v[12:13]
	v_mul_f32_e32 v12, 0xbfb8aa3b, v8
	v_mul_f32_e32 v13, 0xbfb8aa3b, v9
	v_exp_f32_e32 v12, v12
	v_exp_f32_e32 v13, v13
	v_add_f32_e32 v12, 1.0, v12
	v_add_f32_e32 v13, 1.0, v13
	v_rcp_f32_e32 v12, v12
	v_rcp_f32_e32 v13, v13
	s_nop 0
	v_pk_mul_f32 v[8:9], v[8:9], v[12:13]
	s_nop 0
	v_pk_mul_f32 v[8:9], v[0:1], v[8:9]
	v_pk_mul_f32 v[0:1], v[10:11], v[18:19] op_sel_hi:[1,0]
	s_nop 0
	v_mul_f32_e32 v10, 0xbfb8aa3b, v0
	v_mul_f32_e32 v11, 0xbfb8aa3b, v1
	v_exp_f32_e32 v10, v10
	v_exp_f32_e32 v11, v11
	v_add_f32_e32 v10, 1.0, v10
	v_add_f32_e32 v11, 1.0, v11
	v_rcp_f32_e32 v10, v10
	v_rcp_f32_e32 v11, v11
	s_nop 0
	v_pk_mul_f32 v[0:1], v[0:1], v[10:11]
	s_nop 0
	v_pk_mul_f32 v[10:11], v[2:3], v[0:1]
	v_cvt_pk_bf16_f32 v0, v4, v5
	v_mad_i64_i32 v[4:5], s[26:27], v16, s45, v[112:113]
	v_lshl_add_u64 v[4:5], v[4:5], 0, s[24:25]
	v_lshl_add_u64 v[4:5], v[4:5], 0, s[8:9]
	v_cvt_pk_bf16_f32 v1, v6, v7
	v_cvt_pk_bf16_f32 v2, v8, v9
	v_cvt_pk_bf16_f32 v3, v10, v11
	v_lshl_add_u64 v[4:5], v[4:5], 0, v[136:137]
	s_mov_b64 s[24:25], -1
	global_store_dwordx4 v[4:5], v[0:3], off sc0 sc1
	s_cbranch_vccnz .LBB0_970
	s_andn2_b64 vcc, exec, s[4:5]
	s_cbranch_vccnz .LBB0_969
	s_barrier
	s_branch .LBB0_969
